# e28: e25 + out_proj tile re-laid out across the 16-lane rows (permlane16/32 swaps) so every epilogue load/store instruction covers 64 contiguous bytes per row
# speedup vs baseline: 1.0081x; 1.0081x over previous
; __device__ __forceinline__ f32x4 ld_nt(const float* p) { return __builtin_nontemporal_load((const f32x4*)p); }
; #define PG8_STAGE_A(bufoff, gbase) PG8_STAGE(bufoff, gbase, voffA, a64)
; #define PG8_STAGE_B(bufoff, bp, hb, tz) do { if (BMODE == 1 && (tz)) PG8_STAGE(bufoff, (bp) + (hb) * 4096, voffT, t64); else PG8_STAGE(bufoff, (bp) + (hb) * bhstep, voffB, b64); } while (0)
; #define PG8_WAIT_V(n) asm volatile("s_waitcnt vmcnt(" #n ")" ::: "memory")
; #define PG8_BAR __builtin_amdgcn_s_barrier()
; template <class CF, class Epi, class Sched, bool ALIGN_EPI, bool SP2>
; __device__ __forceinline__ void gemm_phase(LAS unsigned char* lds, const char* gA, const char* gB, const Sched& S, const Epi& E, const char* gB2 = nullptr) {
;     ...
;     const char* cA = gA + (size_t)cur.g * CF::A_G + (size_t)cur.pm * CF::A_T; const char* cB = gB + (size_t)cur.g * CF::B_G + (size_t)cur.pn * CF::B_T;
;     const char* cT = BMODE == 1 ? gB2 + (size_t)cur.g * KTG + (size_t)cur.pn * 8192 + 14336 : nullptr;
;     PG8_STAGE_B(PG8_SB(0, 0), cB, 0, false); PG8_STAGE_B(PG8_SB(0, 1), cB, 1, false); PG8_STAGE_A(PG8_SA(0, 0), cA); PG8_STAGE_A(PG8_SA(0, 1), cA + ahstep);
;     if (wr == 1) PG8_BAR;
;     PG8_WAIT_V(2); PG8_BAR;
;     PG8_STAGE_B(PG8_SB(1, 0), cB + bkstep, 0, false); PG8_STAGE_A(PG8_SA(1, 0), cA + akstep); PG8_STAGE_B(PG8_SB(1, 1), cB + bkstep, 1, false);
;     PG8_WAIT_V(6); PG8_BAR;
;     __device__ __forceinline__ void operator()(AccRef acc, const Unit& u, int wr, int wc, int fr, int fq) const {
;         int row0 = u.pm * 256 + wr * 64 + fr; asm volatile("" : "+v"(row0)); int col0 = u.pn * 256 + wc * 32 + 8 * fq; asm volatile("" : "+v"(col0));
;         const float* gate = mod + (size_t)(u.pm >= 32 ? 1 : 0) * 3 * D + 2 * D + col0;
;         f32x4 gv[2][2];
; #pragma unroll
;         for (int bj = 0; bj < 2; ++bj)
; #pragma unroll
;             for (int n = 0; n < 2; ++n) gv[bj][n] = *(const f32x4*)(gate + bj * HALF + n * 4);
; #pragma unroll
;         for (int ai = 0; ai < 2; ++ai)
; #pragma unroll
;             for (int mp = 0; mp < 2; ++mp) { f32x4 xv[2][2][2];
; #pragma unroll
;                 for (int mm = 0; mm < 2; ++mm)
; #pragma unroll
;                     for (int bj = 0; bj < 2; ++bj)
; #pragma unroll
;                         for (int n = 0; n < 2; ++n) xv[mm][bj][n] = ld_nt(x + (size_t)(row0 + ai * HALF + (mp * 2 + mm) * 16) * D + col0 + bj * HALF + n * 4);
.LBB0_1138:
	s_andn2_b64 vcc, exec, s[2:3]
	s_cbranch_vccnz .LBB0_1174
	v_and_b32_e32 v252, 15, v0
	v_lshrrev_b32_e32 v253, 8, v0
	v_lshl_or_b32 v252, v253, 6, v252
	v_bfe_u32 v253, v0, 6, 2
	v_bfe_u32 v251, v0, 4, 2
	v_lshlrev_b32_e32 v251, 2, v251
	v_lshl_or_b32 v253, v253, 5, v251
	v_lshl_add_u32 v250, s58, 8, v252
	v_lshl_or_b32 v251, s22, 8, v253
	v_readlane_b32 s98, v254, 2
	v_readlane_b32 s99, v254, 3
	v_lshlrev_b32_e32 v250, 13, v250
	v_lshlrev_b32_e32 v251, 2, v251
	s_cmp_gt_i32 s58, 31
	s_cselect_b32 vcc_lo, 0x6000, 0
	s_add_u32 s100, s50, vcc_lo
	s_addc_u32 s101, s51, 0
	s_add_u32 s100, s100, 0x104000
	s_addc_u32 s101, s101, 0
	v_add_u32_e32 v250, v250, v251
	s_nop 1
	global_load_dwordx4 v[218:221], v251, s[100:101]
	global_load_dwordx4 v[222:225], v251, s[100:101] offset:64
	global_load_dwordx4 v[226:229], v251, s[100:101] offset:512
	global_load_dwordx4 v[230:233], v251, s[100:101] offset:576
	global_load_dwordx4 v[234:237], v250, s[98:99] nt
	global_load_dwordx4 v[238:241], v250, s[98:99] offset:64 nt
	global_load_dwordx4 v[242:245], v250, s[98:99] offset:512 nt
	global_load_dwordx4 v[246:249], v250, s[98:99] offset:576 nt
	s_add_u32 s0, s50, 0x19800000
	s_addc_u32 s1, s51, 0
	s_add_u32 s33, s50, 0x1400000
	s_addc_u32 s64, s51, 0
	s_lshr_b32 s3, s18, 6
	s_ashr_i32 s59, s58, 31
	s_lshr_b32 s2, s18, 8
	s_lshl_b32 s65, s3, 10
	s_lshl_b64 s[4:5], s[58:59], 20
	v_lshlrev_b32_e32 v2, 4, v0
	v_and_b32_e32 v3, 32, v0
	v_lshrrev_b32_e32 v4, 3, v0
	v_bfe_u32 v1, v0, 2, 4
	s_add_u32 s20, s0, s4
	v_and_or_b32 v5, v4, 48, v1
	v_bitop3_b32 v6, v2, v3, 48 bitop3:0x6c
	v_and_b32_e32 v3, 32, v4
	v_lshrrev_b32_e32 v4, 1, v0
	v_lshrrev_b32_e32 v8, 5, v0
	v_bfe_u32 v9, v0, 2, 2
	s_addc_u32 s21, s1, s5
	s_ashr_i32 s23, s22, 31
	v_and_b32_e32 v7, 64, v0
	v_and_b32_e32 v4, 24, v4
	v_and_or_b32 v8, v8, 4, v9
	s_lshl_b64 s[4:5], s[22:23], 20
	v_or_b32_e32 v2, v6, v7
	v_or3_b32 v3, v8, v3, v4
	s_add_u32 s62, s33, s4
	v_lshl_or_b32 v162, v3, 12, v2
	s_addc_u32 s63, s64, s5
	v_mov_b32_e32 v163, 0
	s_add_i32 s66, s65, 0
	v_lshl_or_b32 v160, v5, 12, v2
	v_lshl_add_u64 v[2:3], s[62:63], 0, v[162:163]
	s_add_i32 m0, s66, 0x10000
	s_mov_b64 s[8:9], 0x40000
	global_load_lds_dwordx4 v162, s[62:63]
	v_lshl_add_u64 v[4:5], v[2:3], 0, s[8:9]
	s_add_i32 m0, s66, 0x12000
	s_mov_b64 s[10:11], 0x80000
	global_load_lds_dwordx4 v[4:5], off
	v_lshl_add_u64 v[4:5], v[2:3], 0, s[10:11]
	s_add_i32 m0, s66, 0x14000
	s_mov_b64 s[12:13], 0xc0000
	global_load_lds_dwordx4 v[4:5], off
	v_lshl_add_u64 v[4:5], v[2:3], 0, s[12:13]
	s_add_i32 m0, s66, 0x16000
	v_mov_b32_e32 v161, v163
	global_load_lds_dwordx4 v[4:5], off
	v_lshl_add_u64 v[4:5], s[20:21], 0, v[160:161]
	s_mov_b32 m0, s66
	s_add_i32 s67, s66, 0x2000
	global_load_lds_dwordx4 v160, s[20:21]
	v_lshl_add_u64 v[8:9], v[4:5], 0, s[8:9]
	s_mov_b32 m0, s67
	s_add_i32 s68, s66, 0x4000
	global_load_lds_dwordx4 v[8:9], off
	v_lshl_add_u64 v[8:9], v[4:5], 0, s[10:11]
	s_mov_b32 m0, s68
	s_add_i32 s69, s66, 0x6000
	global_load_lds_dwordx4 v[8:9], off
	v_lshl_add_u64 v[8:9], v[4:5], 0, s[12:13]
	s_mov_b32 m0, s69
	v_writelane_b32 v254, s82, 18
	global_load_lds_dwordx4 v[8:9], off
	s_nop 0
	v_writelane_b32 v254, s83, 19
	s_cmp_eq_u32 s2, 1
	s_mov_b32 s96, s53
	s_mov_b32 s53, s81
	v_writelane_b32 v254, s78, 36
	s_cselect_b64 s[14:15], -1, 0
	s_cmp_lg_u32 s2, 1
	s_mov_b32 s23, 0
	v_writelane_b32 v254, s79, 37
	s_cbranch_scc1 .LBB0_1141
	s_barrier

; __device__ __forceinline__ f32x4 ld_nt(const float* p) { return __builtin_nontemporal_load((const f32x4*)p); }
; __device__ __forceinline__ u32x4 pack8h(const f32x4 v0, const f32x4 v1) { u32x4 w; w.x = pk_h16(v0[0], v0[1]); w.y = pk_h16(v0[2], v0[3]); w.z = pk_h16(v1[0], v1[1]); w.w = pk_h16(v1[2], v1[3]); return w; }
;     __device__ __forceinline__ void operator()(AccRef acc, const Unit& u, int wr, int wc, int fr, int fq) const {
;         int row0 = u.pm * 256 + wr * 64 + fr; asm volatile("" : "+v"(row0)); int col0 = u.pn * 256 + wc * 32 + 8 * fq; asm volatile("" : "+v"(col0));
;         const float* gate = mod + (size_t)(u.pm >= 32 ? 1 : 0) * 3 * D + 2 * D + col0;
;         f32x4 gv[2][2];
; #pragma unroll
;         for (int bj = 0; bj < 2; ++bj)
; #pragma unroll
;             for (int n = 0; n < 2; ++n) gv[bj][n] = *(const f32x4*)(gate + bj * HALF + n * 4);
; #pragma unroll
;         for (int ai = 0; ai < 2; ++ai)
; #pragma unroll
;             for (int mp = 0; mp < 2; ++mp) { f32x4 xv[2][2][2];
; #pragma unroll
;                 for (int mm = 0; mm < 2; ++mm)
; #pragma unroll
;                     for (int bj = 0; bj < 2; ++bj)
; #pragma unroll
;                         for (int n = 0; n < 2; ++n) xv[mm][bj][n] = ld_nt(x + (size_t)(row0 + ai * HALF + (mp * 2 + mm) * 16) * D + col0 + bj * HALF + n * 4);
;                 __builtin_amdgcn_sched_barrier(0);
; #pragma unroll
;                 for (int mm = 0; mm < 2; ++mm) { const int m = mp * 2 + mm; const int row = row0 + ai * HALF + m * 16; const size_t o = (size_t)row * D + col0; float ss = 0.f;
; #pragma unroll
;                     for (int bj = 0; bj < 2; ++bj) { const f32x4 r0 = xv[mm][bj][0] + gv[bj][0] * acc[ai][bj][m][0], r1 = xv[mm][bj][1] + gv[bj][1] * acc[ai][bj][m][1];
;                         *(u32x4*)(xo + o + bj * HALF) = pack8h(r0, r1);
;                         ss += ((r0[0] * r0[0] + r0[1] * r0[1]) + (r0[2] * r0[2] + r0[3] * r0[3])) + ((r1[0] * r1[0] + r1[1] * r1[1]) + (r1[2] * r1[2] + r1[3] * r1[3])); }
.LBB0_1154:
	v_lshl_add_u32 v172, s58, 8, v178
	v_lshrrev_b32_e32 v170, 4, v184
	v_and_b32_e32 v171, 0x60, v180
	v_lshl_or_b32 v170, v170, 2, v171
	v_lshl_or_b32 v170, s22, 8, v170
	v_readlane_b32 s80, v254, 2
	v_readlane_b32 s81, v254, 3
	v_lshlrev_b32_e32 v173, 13, v172
	v_lshlrev_b32_e32 v187, 7, v172
	v_lshlrev_b32_e32 v171, 2, v170
	v_lshl_add_u32 v173, v170, 2, v173
	s_lshl_b32 s18, s22, 2
	s_add_u32 s18, s18, s72
	s_lshl_b32 s18, s18, 2
	s_add_u32 s88, s26, s18
	s_addc_u32 s89, s27, 0
	v_xor_b32_e32 v186, 16, v184
	v_xor_b32_e32 v185, 32, v184
	v_lshrrev_b32_e32 v174, 4, v184
	v_lshlrev_b32_e32 v186, 2, v186
	v_lshlrev_b32_e32 v185, 2, v185
	v_lshl_add_u32 v174, v174, 5, v187
	s_mov_b32 s94, 0x3a000000
	s_mov_b32 s95, 0x358637bd
	s_mov_b64 s[82:83], s[48:49]
	s_lshr_b32 s59, s65, 10
	global_load_dwordx4 v[144:147], v171, s[46:47]
	global_load_dwordx4 v[148:151], v171, s[46:47] offset:64
	global_load_dwordx4 v[152:155], v171, s[46:47] offset:512
	global_load_dwordx4 v[156:159], v171, s[46:47] offset:576
	s_add_u32 s84, s80, 0x20000
	s_addc_u32 s85, s81, 0
	global_load_dwordx4 v[188:191], v173, s[84:85] nt
	global_load_dwordx4 v[192:195], v173, s[84:85] offset:64 nt
	global_load_dwordx4 v[196:199], v173, s[84:85] offset:512 nt
	global_load_dwordx4 v[200:203], v173, s[84:85] offset:576 nt
	s_add_u32 s84, s80, 0x40000
	s_addc_u32 s85, s81, 0
	global_load_dwordx4 v[104:107], v173, s[84:85] nt
	global_load_dwordx4 v[108:111], v173, s[84:85] offset:64 nt
	global_load_dwordx4 v[112:115], v173, s[84:85] offset:512 nt
	global_load_dwordx4 v[120:123], v173, s[84:85] offset:576 nt
	v_permlane16_swap_b32_e32 v140, v136
	v_permlane16_swap_b32_e32 v141, v137
	v_permlane16_swap_b32_e32 v142, v138
	v_permlane16_swap_b32_e32 v143, v139
	v_permlane32_swap_b32_e32 v140, v136
	v_permlane32_swap_b32_e32 v141, v137
	v_permlane32_swap_b32_e32 v142, v138
	v_permlane32_swap_b32_e32 v143, v139
	v_permlane16_swap_b32_e32 v132, v128
	v_permlane16_swap_b32_e32 v133, v129
	v_permlane16_swap_b32_e32 v134, v130
	v_permlane16_swap_b32_e32 v135, v131
	v_permlane32_swap_b32_e32 v132, v128
	v_permlane32_swap_b32_e32 v133, v129
	v_permlane32_swap_b32_e32 v134, v130
	v_permlane32_swap_b32_e32 v135, v131
	v_permlane16_swap_b32_e32 v124, v116
	v_permlane16_swap_b32_e32 v125, v117
	v_permlane16_swap_b32_e32 v126, v118
	v_permlane16_swap_b32_e32 v127, v119
	v_permlane32_swap_b32_e32 v124, v116
	v_permlane32_swap_b32_e32 v125, v117
	v_permlane32_swap_b32_e32 v126, v118
	v_permlane32_swap_b32_e32 v127, v119
	v_permlane16_swap_b32_e32 v100, v96
	v_permlane16_swap_b32_e32 v101, v97
	v_permlane16_swap_b32_e32 v102, v98
	v_permlane16_swap_b32_e32 v103, v99
	v_permlane32_swap_b32_e32 v100, v96
	v_permlane32_swap_b32_e32 v101, v97
	v_permlane32_swap_b32_e32 v102, v98
	v_permlane32_swap_b32_e32 v103, v99
	s_waitcnt vmcnt(12)
	v_pk_fma_f32 v[140:141], v[140:141], v[218:219], v[234:235]
	v_pk_fma_f32 v[142:143], v[142:143], v[220:221], v[236:237]
	v_pk_fma_f32 v[136:137], v[136:137], v[222:223], v[238:239]
	v_pk_fma_f32 v[138:139], v[138:139], v[224:225], v[240:241]
	v_pk_fma_f32 v[132:133], v[132:133], v[226:227], v[242:243]
	v_pk_fma_f32 v[134:135], v[134:135], v[228:229], v[244:245]
	v_pk_fma_f32 v[128:129], v[128:129], v[230:231], v[246:247]
	v_pk_fma_f32 v[130:131], v[130:131], v[232:233], v[248:249]
	s_add_u32 s84, s80, 0x60000
	s_addc_u32 s85, s81, 0
	global_load_dwordx4 v[234:237], v173, s[84:85] nt
	global_load_dwordx4 v[238:241], v173, s[84:85] offset:64 nt
	global_load_dwordx4 v[242:245], v173, s[84:85] offset:512 nt
	global_load_dwordx4 v[246:249], v173, s[84:85] offset:576 nt
	v_pk_mul_f32 v[176:177], v[140:141], v[140:141]
	v_pk_fma_f32 v[176:177], v[142:143], v[142:143], v[176:177]
	v_pk_fma_f32 v[176:177], v[136:137], v[136:137], v[176:177]
	v_pk_fma_f32 v[176:177], v[138:139], v[138:139], v[176:177]
	v_pk_fma_f32 v[176:177], v[132:133], v[132:133], v[176:177]
	v_pk_fma_f32 v[176:177], v[134:135], v[134:135], v[176:177]
	v_pk_fma_f32 v[176:177], v[128:129], v[128:129], v[176:177]
	v_pk_fma_f32 v[176:177], v[130:131], v[130:131], v[176:177]
	v_add_f32_e32 v204, v176, v177
	v_permlane16_swap_b32_e32 v92, v88
	v_permlane16_swap_b32_e32 v93, v89
	v_permlane16_swap_b32_e32 v94, v90
	v_permlane16_swap_b32_e32 v95, v91
	v_permlane32_swap_b32_e32 v92, v88
	v_permlane32_swap_b32_e32 v93, v89
	v_permlane32_swap_b32_e32 v94, v90
	v_permlane32_swap_b32_e32 v95, v91
	v_permlane16_swap_b32_e32 v84, v80
	v_permlane16_swap_b32_e32 v85, v81
	v_permlane16_swap_b32_e32 v86, v82
	v_permlane16_swap_b32_e32 v87, v83
	v_permlane32_swap_b32_e32 v84, v80
	v_permlane32_swap_b32_e32 v85, v81
	v_permlane32_swap_b32_e32 v86, v82
	v_permlane32_swap_b32_e32 v87, v83
	s_waitcnt vmcnt(8)
; __device__ __forceinline__ f32x4 ld_nt(const float* p) { return __builtin_nontemporal_load((const f32x4*)p); }
; __device__ __forceinline__ u32x4 pack8h(const f32x4 v0, const f32x4 v1) { u32x4 w; w.x = pk_h16(v0[0], v0[1]); w.y = pk_h16(v0[2], v0[3]); w.z = pk_h16(v1[0], v1[1]); w.w = pk_h16(v1[2], v1[3]); return w; }
;     __device__ __forceinline__ void operator()(AccRef acc, const Unit& u, int wr, int wc, int fr, int fq) const {
;     ...
;                         for (int n = 0; n < 2; ++n) xv[mm][bj][n] = ld_nt(x + (size_t)(row0 + ai * HALF + (mp * 2 + mm) * 16) * D + col0 + bj * HALF + n * 4);
;                 __builtin_amdgcn_sched_barrier(0);
; #pragma unroll
;                 for (int mm = 0; mm < 2; ++mm) { const int m = mp * 2 + mm; const int row = row0 + ai * HALF + m * 16; const size_t o = (size_t)row * D + col0; float ss = 0.f;
; #pragma unroll
;                     for (int bj = 0; bj < 2; ++bj) { const f32x4 r0 = xv[mm][bj][0] + gv[bj][0] * acc[ai][bj][m][0], r1 = xv[mm][bj][1] + gv[bj][1] * acc[ai][bj][m][1];
;                         *(u32x4*)(xo + o + bj * HALF) = pack8h(r0, r1);
;                         ss += ((r0[0] * r0[0] + r0[1] * r0[1]) + (r0[2] * r0[2] + r0[3] * r0[3])) + ((r1[0] * r1[0] + r1[1] * r1[1]) + (r1[2] * r1[2] + r1[3] * r1[3])); }
	v_pk_fma_f32 v[124:125], v[124:125], v[218:219], v[188:189]
	v_pk_fma_f32 v[126:127], v[126:127], v[220:221], v[190:191]
	v_pk_fma_f32 v[116:117], v[116:117], v[222:223], v[192:193]
	v_pk_fma_f32 v[118:119], v[118:119], v[224:225], v[194:195]
	v_pk_fma_f32 v[100:101], v[100:101], v[226:227], v[196:197]
	v_pk_fma_f32 v[102:103], v[102:103], v[228:229], v[198:199]
	v_pk_fma_f32 v[96:97], v[96:97], v[230:231], v[200:201]
	v_pk_fma_f32 v[98:99], v[98:99], v[232:233], v[202:203]
	s_add_u32 s84, s80, 0x100000
	s_addc_u32 s85, s81, 0
	global_load_dwordx4 v[188:191], v173, s[84:85] nt
	global_load_dwordx4 v[192:195], v173, s[84:85] offset:64 nt
	global_load_dwordx4 v[196:199], v173, s[84:85] offset:512 nt
	global_load_dwordx4 v[200:203], v173, s[84:85] offset:576 nt
	v_pk_mul_f32 v[176:177], v[124:125], v[124:125]
	v_pk_fma_f32 v[176:177], v[126:127], v[126:127], v[176:177]
	v_pk_fma_f32 v[176:177], v[116:117], v[116:117], v[176:177]
	v_pk_fma_f32 v[176:177], v[118:119], v[118:119], v[176:177]
	v_pk_fma_f32 v[176:177], v[100:101], v[100:101], v[176:177]
	v_pk_fma_f32 v[176:177], v[102:103], v[102:103], v[176:177]
	v_pk_fma_f32 v[176:177], v[96:97], v[96:97], v[176:177]
	v_pk_fma_f32 v[176:177], v[98:99], v[98:99], v[176:177]
	v_add_f32_e32 v205, v176, v177
	v_permlane16_swap_b32_e32 v76, v72
	v_permlane16_swap_b32_e32 v77, v73
	v_permlane16_swap_b32_e32 v78, v74
	v_permlane16_swap_b32_e32 v79, v75
	v_permlane32_swap_b32_e32 v76, v72
	v_permlane32_swap_b32_e32 v77, v73
	v_permlane32_swap_b32_e32 v78, v74
	v_permlane32_swap_b32_e32 v79, v75
	v_permlane16_swap_b32_e32 v68, v64
	v_permlane16_swap_b32_e32 v69, v65
	v_permlane16_swap_b32_e32 v70, v66
	v_permlane16_swap_b32_e32 v71, v67
	v_permlane32_swap_b32_e32 v68, v64
	v_permlane32_swap_b32_e32 v69, v65
	v_permlane32_swap_b32_e32 v70, v66
	v_permlane32_swap_b32_e32 v71, v67
	s_waitcnt vmcnt(8)
	v_pk_fma_f32 v[92:93], v[92:93], v[218:219], v[104:105]
	v_pk_fma_f32 v[94:95], v[94:95], v[220:221], v[106:107]
	v_pk_fma_f32 v[88:89], v[88:89], v[222:223], v[108:109]
	v_pk_fma_f32 v[90:91], v[90:91], v[224:225], v[110:111]
	v_pk_fma_f32 v[84:85], v[84:85], v[226:227], v[112:113]
	v_pk_fma_f32 v[86:87], v[86:87], v[228:229], v[114:115]
	v_pk_fma_f32 v[80:81], v[80:81], v[230:231], v[120:121]
	v_pk_fma_f32 v[82:83], v[82:83], v[232:233], v[122:123]
	s_add_u32 s84, s80, 0x120000
	s_addc_u32 s85, s81, 0
	global_load_dwordx4 v[104:107], v173, s[84:85] nt
	global_load_dwordx4 v[108:111], v173, s[84:85] offset:64 nt
	global_load_dwordx4 v[112:115], v173, s[84:85] offset:512 nt
	global_load_dwordx4 v[120:123], v173, s[84:85] offset:576 nt
	v_pk_mul_f32 v[176:177], v[92:93], v[92:93]
	v_pk_fma_f32 v[176:177], v[94:95], v[94:95], v[176:177]
	v_pk_fma_f32 v[176:177], v[88:89], v[88:89], v[176:177]
	v_pk_fma_f32 v[176:177], v[90:91], v[90:91], v[176:177]
	v_pk_fma_f32 v[176:177], v[84:85], v[84:85], v[176:177]
	v_pk_fma_f32 v[176:177], v[86:87], v[86:87], v[176:177]
	v_pk_fma_f32 v[176:177], v[80:81], v[80:81], v[176:177]
	v_pk_fma_f32 v[176:177], v[82:83], v[82:83], v[176:177]
	v_add_f32_e32 v206, v176, v177
	v_permlane16_swap_b32_e32 v60, v56
	v_permlane16_swap_b32_e32 v61, v57
	v_permlane16_swap_b32_e32 v62, v58
	v_permlane16_swap_b32_e32 v63, v59
	v_permlane32_swap_b32_e32 v60, v56
	v_permlane32_swap_b32_e32 v61, v57
	v_permlane32_swap_b32_e32 v62, v58
	v_permlane32_swap_b32_e32 v63, v59
	v_permlane16_swap_b32_e32 v52, v48
	v_permlane16_swap_b32_e32 v53, v49
	v_permlane16_swap_b32_e32 v54, v50
	v_permlane16_swap_b32_e32 v55, v51
	v_permlane32_swap_b32_e32 v52, v48
	v_permlane32_swap_b32_e32 v53, v49
	v_permlane32_swap_b32_e32 v54, v50
	v_permlane32_swap_b32_e32 v55, v51
	s_waitcnt vmcnt(8)
	v_pk_fma_f32 v[76:77], v[76:77], v[218:219], v[234:235]
	v_pk_fma_f32 v[78:79], v[78:79], v[220:221], v[236:237]
	v_pk_fma_f32 v[72:73], v[72:73], v[222:223], v[238:239]
	v_pk_fma_f32 v[74:75], v[74:75], v[224:225], v[240:241]
	v_pk_fma_f32 v[68:69], v[68:69], v[226:227], v[242:243]
	v_pk_fma_f32 v[70:71], v[70:71], v[228:229], v[244:245]
	v_pk_fma_f32 v[64:65], v[64:65], v[230:231], v[246:247]
	v_pk_fma_f32 v[66:67], v[66:67], v[232:233], v[248:249]
	s_add_u32 s84, s80, 0x140000
	s_addc_u32 s85, s81, 0
	global_load_dwordx4 v[234:237], v173, s[84:85] nt
	global_load_dwordx4 v[238:241], v173, s[84:85] offset:64 nt
	global_load_dwordx4 v[242:245], v173, s[84:85] offset:512 nt
	global_load_dwordx4 v[246:249], v173, s[84:85] offset:576 nt
	v_pk_mul_f32 v[176:177], v[76:77], v[76:77]
	v_pk_fma_f32 v[176:177], v[78:79], v[78:79], v[176:177]
	v_pk_fma_f32 v[176:177], v[72:73], v[72:73], v[176:177]
	v_pk_fma_f32 v[176:177], v[74:75], v[74:75], v[176:177]
	v_pk_fma_f32 v[176:177], v[68:69], v[68:69], v[176:177]
	v_pk_fma_f32 v[176:177], v[70:71], v[70:71], v[176:177]
	v_pk_fma_f32 v[176:177], v[64:65], v[64:65], v[176:177]
	v_pk_fma_f32 v[176:177], v[66:67], v[66:67], v[176:177]
	v_add_f32_e32 v207, v176, v177
	ds_bpermute_b32 v214, v186, v204
	ds_bpermute_b32 v215, v186, v205
	ds_bpermute_b32 v216, v186, v206
	ds_bpermute_b32 v217, v186, v207
	s_waitcnt lgkmcnt(0)
	v_pk_add_f32 v[204:205], v[204:205], v[214:215]
	v_pk_add_f32 v[206:207], v[206:207], v[216:217]
	ds_bpermute_b32 v214, v185, v204
	ds_bpermute_b32 v215, v185, v205
	ds_bpermute_b32 v216, v185, v206
	ds_bpermute_b32 v217, v185, v207
	s_waitcnt lgkmcnt(0)
; __device__ __forceinline__ u32x4 pack8h(const f32x4 v0, const f32x4 v1) { u32x4 w; w.x = pk_h16(v0[0], v0[1]); w.y = pk_h16(v0[2], v0[3]); w.z = pk_h16(v1[0], v1[1]); w.w = pk_h16(v1[2], v1[3]); return w; }
;     __device__ __forceinline__ void operator()(AccRef acc, const Unit& u, int wr, int wc, int fr, int fq) const {
;     ...
;                 for (int mm = 0; mm < 2; ++mm) { const int m = mp * 2 + mm; const int row = row0 + ai * HALF + m * 16; const size_t o = (size_t)row * D + col0; float ss = 0.f;
; #pragma unroll
;                     for (int bj = 0; bj < 2; ++bj) { const f32x4 r0 = xv[mm][bj][0] + gv[bj][0] * acc[ai][bj][m][0], r1 = xv[mm][bj][1] + gv[bj][1] * acc[ai][bj][m][1];
;                         *(u32x4*)(xo + o + bj * HALF) = pack8h(r0, r1);
;                         ss += ((r0[0] * r0[0] + r0[1] * r0[1]) + (r0[2] * r0[2] + r0[3] * r0[3])) + ((r1[0] * r1[0] + r1[1] * r1[1]) + (r1[2] * r1[2] + r1[3] * r1[3])); }
;                     ss += __shfl_xor(ss, 16); ss += __shfl_xor(ss, 32);
;                     if (fq == 0) rowss[(size_t)row * 32 + u.pn * 4 + wc] = ss; } }
	v_pk_add_f32 v[204:205], v[204:205], v[214:215]
	v_pk_add_f32 v[206:207], v[206:207], v[216:217]
	s_and_saveexec_b64 s[20:21], s[2:3]
	s_mov_b64 s[90:91], s[88:89]
	global_store_dword v187, v204, s[90:91] sc0 sc1
	s_add_u32 s90, s88, 0x800
	s_addc_u32 s91, s89, 0
	global_store_dword v187, v205, s[90:91] sc0 sc1
	s_add_u32 s90, s88, 0x1000
	s_addc_u32 s91, s89, 0
	global_store_dword v187, v206, s[90:91] sc0 sc1
	s_add_u32 s90, s88, 0x1800
	s_addc_u32 s91, s89, 0
	global_store_dword v187, v207, s[90:91] sc0 sc1
	s_or_b64 exec, exec, s[20:21]
	s_waitcnt vmcnt(12)
	v_permlane16_swap_b32_e32 v44, v40
	v_permlane16_swap_b32_e32 v45, v41
	v_permlane16_swap_b32_e32 v46, v42
	v_permlane16_swap_b32_e32 v47, v43
	v_permlane32_swap_b32_e32 v44, v40
	v_permlane32_swap_b32_e32 v45, v41
	v_permlane32_swap_b32_e32 v46, v42
	v_permlane32_swap_b32_e32 v47, v43
	v_permlane16_swap_b32_e32 v36, v32
	v_permlane16_swap_b32_e32 v37, v33
	v_permlane16_swap_b32_e32 v38, v34
	v_permlane16_swap_b32_e32 v39, v35
	v_permlane32_swap_b32_e32 v36, v32
	v_permlane32_swap_b32_e32 v37, v33
	v_permlane32_swap_b32_e32 v38, v34
	v_permlane32_swap_b32_e32 v39, v35
	v_pk_fma_f32 v[60:61], v[60:61], v[218:219], v[188:189]
	v_pk_fma_f32 v[62:63], v[62:63], v[220:221], v[190:191]
	v_pk_fma_f32 v[56:57], v[56:57], v[222:223], v[192:193]
	v_pk_fma_f32 v[58:59], v[58:59], v[224:225], v[194:195]
	v_pk_fma_f32 v[52:53], v[52:53], v[226:227], v[196:197]
	v_pk_fma_f32 v[54:55], v[54:55], v[228:229], v[198:199]
	v_pk_fma_f32 v[48:49], v[48:49], v[230:231], v[200:201]
	v_pk_fma_f32 v[50:51], v[50:51], v[232:233], v[202:203]
	s_add_u32 s84, s80, 0x160000
	s_addc_u32 s85, s81, 0
	global_load_dwordx4 v[188:191], v173, s[84:85] nt
	global_load_dwordx4 v[192:195], v173, s[84:85] offset:64 nt
	global_load_dwordx4 v[196:199], v173, s[84:85] offset:512 nt
	global_load_dwordx4 v[200:203], v173, s[84:85] offset:576 nt
	v_pk_mul_f32 v[176:177], v[60:61], v[60:61]
	v_pk_fma_f32 v[176:177], v[62:63], v[62:63], v[176:177]
	v_pk_fma_f32 v[176:177], v[56:57], v[56:57], v[176:177]
	v_pk_fma_f32 v[176:177], v[58:59], v[58:59], v[176:177]
	v_pk_fma_f32 v[176:177], v[52:53], v[52:53], v[176:177]
	v_pk_fma_f32 v[176:177], v[54:55], v[54:55], v[176:177]
	v_pk_fma_f32 v[176:177], v[48:49], v[48:49], v[176:177]
	v_pk_fma_f32 v[176:177], v[50:51], v[50:51], v[176:177]
	v_add_f32_e32 v208, v176, v177
	s_waitcnt vmcnt(12)
	v_permlane16_swap_b32_e32 v28, v24
	v_permlane16_swap_b32_e32 v29, v25
	v_permlane16_swap_b32_e32 v30, v26
	v_permlane16_swap_b32_e32 v31, v27
	v_permlane32_swap_b32_e32 v28, v24
	v_permlane32_swap_b32_e32 v29, v25
	v_permlane32_swap_b32_e32 v30, v26
	v_permlane32_swap_b32_e32 v31, v27
	v_permlane16_swap_b32_e32 v20, v16
	v_permlane16_swap_b32_e32 v21, v17
	v_permlane16_swap_b32_e32 v22, v18
	v_permlane16_swap_b32_e32 v23, v19
	v_permlane32_swap_b32_e32 v20, v16
	v_permlane32_swap_b32_e32 v21, v17
	v_permlane32_swap_b32_e32 v22, v18
	v_permlane32_swap_b32_e32 v23, v19
	v_pk_fma_f32 v[44:45], v[44:45], v[218:219], v[104:105]
	v_pk_fma_f32 v[46:47], v[46:47], v[220:221], v[106:107]
	v_pk_fma_f32 v[40:41], v[40:41], v[222:223], v[108:109]
	v_pk_fma_f32 v[42:43], v[42:43], v[224:225], v[110:111]
	v_pk_fma_f32 v[36:37], v[36:37], v[226:227], v[112:113]
	v_pk_fma_f32 v[38:39], v[38:39], v[228:229], v[114:115]
	v_pk_fma_f32 v[32:33], v[32:33], v[230:231], v[120:121]
	v_pk_fma_f32 v[34:35], v[34:35], v[232:233], v[122:123]
	v_pk_mul_f32 v[176:177], v[44:45], v[44:45]
	v_pk_fma_f32 v[176:177], v[46:47], v[46:47], v[176:177]
	v_pk_fma_f32 v[176:177], v[40:41], v[40:41], v[176:177]
	v_pk_fma_f32 v[176:177], v[42:43], v[42:43], v[176:177]
	v_pk_fma_f32 v[176:177], v[36:37], v[36:37], v[176:177]
	v_pk_fma_f32 v[176:177], v[38:39], v[38:39], v[176:177]
	v_pk_fma_f32 v[176:177], v[32:33], v[32:33], v[176:177]
	v_pk_fma_f32 v[176:177], v[34:35], v[34:35], v[176:177]
	v_add_f32_e32 v209, v176, v177
	s_waitcnt vmcnt(4)
	v_permlane16_swap_b32_e32 v12, v8
	v_permlane16_swap_b32_e32 v13, v9
	v_permlane16_swap_b32_e32 v14, v10
	v_permlane16_swap_b32_e32 v15, v11
	v_permlane32_swap_b32_e32 v12, v8
	v_permlane32_swap_b32_e32 v13, v9
	v_permlane32_swap_b32_e32 v14, v10
	v_permlane32_swap_b32_e32 v15, v11
	v_permlane16_swap_b32_e32 v4, v0
	v_permlane16_swap_b32_e32 v5, v1
	v_permlane16_swap_b32_e32 v6, v2
	v_permlane16_swap_b32_e32 v7, v3
	v_permlane32_swap_b32_e32 v4, v0
	v_permlane32_swap_b32_e32 v5, v1
	v_permlane32_swap_b32_e32 v6, v2
	v_permlane32_swap_b32_e32 v7, v3
	v_pk_fma_f32 v[28:29], v[28:29], v[218:219], v[234:235]
	v_pk_fma_f32 v[30:31], v[30:31], v[220:221], v[236:237]
	v_pk_fma_f32 v[24:25], v[24:25], v[222:223], v[238:239]
	v_pk_fma_f32 v[26:27], v[26:27], v[224:225], v[240:241]
	v_pk_fma_f32 v[20:21], v[20:21], v[226:227], v[242:243]
	v_pk_fma_f32 v[22:23], v[22:23], v[228:229], v[244:245]
	v_pk_fma_f32 v[16:17], v[16:17], v[230:231], v[246:247]
	v_pk_fma_f32 v[18:19], v[18:19], v[232:233], v[248:249]
	v_pk_mul_f32 v[176:177], v[28:29], v[28:29]
	v_pk_fma_f32 v[176:177], v[30:31], v[30:31], v[176:177]
	v_pk_fma_f32 v[176:177], v[24:25], v[24:25], v[176:177]
	v_pk_fma_f32 v[176:177], v[26:27], v[26:27], v[176:177]
	v_pk_fma_f32 v[176:177], v[20:21], v[20:21], v[176:177]
	v_pk_fma_f32 v[176:177], v[22:23], v[22:23], v[176:177]
	v_pk_fma_f32 v[176:177], v[16:17], v[16:17], v[176:177]
	v_pk_fma_f32 v[176:177], v[18:19], v[18:19], v[176:177]
	v_add_f32_e32 v210, v176, v177
	s_barrier
	s_cmp_lg_u32 s59, 0
	s_cbranch_scc1 .Lepi_a1
	s_lshl_b32 s18, s58, 6
	s_add_u32 s18, s18, 0xc000
	s_mov_b64 exec, 1
	v_mov_b32_e32 v175, s18
	v_mov_b32_e32 v255, 1
	global_atomic_add v175, v255, s[50:51]
	s_mov_b64 exec, -1

; __device__ __forceinline__ void unpack8h(const u32x4 w, f32x4& v0, f32x4& v1) { v0 = (f32x4){h16lo(w.x), h16hi(w.x), h16lo(w.y), h16hi(w.y)}; v1 = (f32x4){h16lo(w.z), h16hi(w.z), h16lo(w.w), h16hi(w.w)}; }
; __device__ __forceinline__ void final_rows(int gw, int lane, const f16* xo, float* out, const float* fg, const float* rowss) {
;     ...
;         for (int rr = 0; rr < 4; ++rr) { const float rstd = rsqrtf(wave_sum(part[rr]) * (1.f / D) + EPS); float* rp = out + (size_t)(r0 + rr) * D + 8 * lane;
; #pragma unroll
;             for (int j = 0; j < 4; ++j) { f32x4 a0, a1; unpack8h(v[rr][j], a0, a1); *(f32x4*)(rp + 512 * j) = a0 * rstd * g4[j][0]; *(f32x4*)(rp + 512 * j + 4) = a1 * rstd * g4[j][1]; } }
.Lepi_d1:
	s_mov_b64 s[86:87], s[82:83]
	v_pk_mul_f32 v[140:141], v[140:141], v[204:205] op_sel_hi:[1,0]
	v_pk_mul_f32 v[142:143], v[142:143], v[204:205] op_sel_hi:[1,0]
	v_pk_mul_f32 v[140:141], v[140:141], v[144:145]
	v_pk_mul_f32 v[142:143], v[142:143], v[146:147]
	v_pk_mul_f32 v[136:137], v[136:137], v[204:205] op_sel_hi:[1,0]
	v_pk_mul_f32 v[138:139], v[138:139], v[204:205] op_sel_hi:[1,0]
	v_pk_mul_f32 v[136:137], v[136:137], v[148:149]
	v_pk_mul_f32 v[138:139], v[138:139], v[150:151]
	v_pk_mul_f32 v[132:133], v[132:133], v[204:205] op_sel_hi:[1,0]
	v_pk_mul_f32 v[134:135], v[134:135], v[204:205] op_sel_hi:[1,0]
	v_pk_mul_f32 v[132:133], v[132:133], v[152:153]
	v_pk_mul_f32 v[134:135], v[134:135], v[154:155]
	v_pk_mul_f32 v[128:129], v[128:129], v[204:205] op_sel_hi:[1,0]
	v_pk_mul_f32 v[130:131], v[130:131], v[204:205] op_sel_hi:[1,0]
	v_pk_mul_f32 v[128:129], v[128:129], v[156:157]
	v_pk_mul_f32 v[130:131], v[130:131], v[158:159]
	global_store_dwordx4 v173, v[140:143], s[86:87]
	global_store_dwordx4 v173, v[136:139], s[86:87] offset:64
	global_store_dwordx4 v173, v[132:135], s[86:87] offset:512
	global_store_dwordx4 v173, v[128:131], s[86:87] offset:576
	s_add_u32 s86, s82, 0x20000
	s_addc_u32 s87, s83, 0
	v_pk_mul_f32 v[124:125], v[124:125], v[206:207] op_sel_hi:[1,0]
	v_pk_mul_f32 v[126:127], v[126:127], v[206:207] op_sel_hi:[1,0]
	v_pk_mul_f32 v[124:125], v[124:125], v[144:145]
	v_pk_mul_f32 v[126:127], v[126:127], v[146:147]
	v_pk_mul_f32 v[116:117], v[116:117], v[206:207] op_sel_hi:[1,0]
	v_pk_mul_f32 v[118:119], v[118:119], v[206:207] op_sel_hi:[1,0]
	v_pk_mul_f32 v[116:117], v[116:117], v[148:149]
	v_pk_mul_f32 v[118:119], v[118:119], v[150:151]
	v_pk_mul_f32 v[100:101], v[100:101], v[206:207] op_sel_hi:[1,0]
	v_pk_mul_f32 v[102:103], v[102:103], v[206:207] op_sel_hi:[1,0]
	v_pk_mul_f32 v[100:101], v[100:101], v[152:153]
	v_pk_mul_f32 v[102:103], v[102:103], v[154:155]
	v_pk_mul_f32 v[96:97], v[96:97], v[206:207] op_sel_hi:[1,0]
	v_pk_mul_f32 v[98:99], v[98:99], v[206:207] op_sel_hi:[1,0]
	v_pk_mul_f32 v[96:97], v[96:97], v[156:157]
	v_pk_mul_f32 v[98:99], v[98:99], v[158:159]
	global_store_dwordx4 v173, v[124:127], s[86:87]
	global_store_dwordx4 v173, v[116:119], s[86:87] offset:64
	global_store_dwordx4 v173, v[100:103], s[86:87] offset:512
	global_store_dwordx4 v173, v[96:99], s[86:87] offset:576
	s_add_u32 s86, s82, 0x40000
	s_addc_u32 s87, s83, 0
	v_pk_mul_f32 v[92:93], v[92:93], v[208:209] op_sel_hi:[1,0]
	v_pk_mul_f32 v[94:95], v[94:95], v[208:209] op_sel_hi:[1,0]
	v_pk_mul_f32 v[92:93], v[92:93], v[144:145]
	v_pk_mul_f32 v[94:95], v[94:95], v[146:147]
	v_pk_mul_f32 v[88:89], v[88:89], v[208:209] op_sel_hi:[1,0]
	v_pk_mul_f32 v[90:91], v[90:91], v[208:209] op_sel_hi:[1,0]
	v_pk_mul_f32 v[88:89], v[88:89], v[148:149]
	v_pk_mul_f32 v[90:91], v[90:91], v[150:151]
	v_pk_mul_f32 v[84:85], v[84:85], v[208:209] op_sel_hi:[1,0]
	v_pk_mul_f32 v[86:87], v[86:87], v[208:209] op_sel_hi:[1,0]
	v_pk_mul_f32 v[84:85], v[84:85], v[152:153]
	v_pk_mul_f32 v[86:87], v[86:87], v[154:155]
	v_pk_mul_f32 v[80:81], v[80:81], v[208:209] op_sel_hi:[1,0]
	v_pk_mul_f32 v[82:83], v[82:83], v[208:209] op_sel_hi:[1,0]
	v_pk_mul_f32 v[80:81], v[80:81], v[156:157]
	v_pk_mul_f32 v[82:83], v[82:83], v[158:159]
	global_store_dwordx4 v173, v[92:95], s[86:87]
	global_store_dwordx4 v173, v[88:91], s[86:87] offset:64
	global_store_dwordx4 v173, v[84:87], s[86:87] offset:512
	global_store_dwordx4 v173, v[80:83], s[86:87] offset:576
	s_add_u32 s86, s82, 0x60000
	s_addc_u32 s87, s83, 0
	v_pk_mul_f32 v[76:77], v[76:77], v[210:211] op_sel_hi:[1,0]
	v_pk_mul_f32 v[78:79], v[78:79], v[210:211] op_sel_hi:[1,0]
	v_pk_mul_f32 v[76:77], v[76:77], v[144:145]
	v_pk_mul_f32 v[78:79], v[78:79], v[146:147]
	v_pk_mul_f32 v[72:73], v[72:73], v[210:211] op_sel_hi:[1,0]
	v_pk_mul_f32 v[74:75], v[74:75], v[210:211] op_sel_hi:[1,0]
	v_pk_mul_f32 v[72:73], v[72:73], v[148:149]
	v_pk_mul_f32 v[74:75], v[74:75], v[150:151]
	v_pk_mul_f32 v[68:69], v[68:69], v[210:211] op_sel_hi:[1,0]
	v_pk_mul_f32 v[70:71], v[70:71], v[210:211] op_sel_hi:[1,0]
	v_pk_mul_f32 v[68:69], v[68:69], v[152:153]
	v_pk_mul_f32 v[70:71], v[70:71], v[154:155]
	v_pk_mul_f32 v[64:65], v[64:65], v[210:211] op_sel_hi:[1,0]
	v_pk_mul_f32 v[66:67], v[66:67], v[210:211] op_sel_hi:[1,0]
	v_pk_mul_f32 v[64:65], v[64:65], v[156:157]
	v_pk_mul_f32 v[66:67], v[66:67], v[158:159]
	global_store_dwordx4 v173, v[76:79], s[86:87]
	global_store_dwordx4 v173, v[72:75], s[86:87] offset:64
	global_store_dwordx4 v173, v[68:71], s[86:87] offset:512
	global_store_dwordx4 v173, v[64:67], s[86:87] offset:576
; __device__ __forceinline__ void unpack8h(const u32x4 w, f32x4& v0, f32x4& v1) { v0 = (f32x4){h16lo(w.x), h16hi(w.x), h16lo(w.y), h16hi(w.y)}; v1 = (f32x4){h16lo(w.z), h16hi(w.z), h16lo(w.w), h16hi(w.w)}; }
; __device__ __forceinline__ void final_rows(int gw, int lane, const f16* xo, float* out, const float* fg, const float* rowss) {
;     ...
;         for (int rr = 0; rr < 4; ++rr) { part[rr] = lane < 32 ? rowss[(size_t)(r0 + rr) * 32 + lane] : 0.f;
; #pragma unroll
;             for (int j = 0; j < 4; ++j) v[rr][j] = *(const u32x4*)(xo + (size_t)(r0 + rr) * D + 512 * j + 8 * lane); }
;         __builtin_amdgcn_sched_barrier(0);
; #pragma unroll
;         for (int rr = 0; rr < 4; ++rr) { const float rstd = rsqrtf(wave_sum(part[rr]) * (1.f / D) + EPS); float* rp = out + (size_t)(r0 + rr) * D + 8 * lane;
; #pragma unroll
;             for (int j = 0; j < 4; ++j) { f32x4 a0, a1; unpack8h(v[rr][j], a0, a1); *(f32x4*)(rp + 512 * j) = a0 * rstd * g4[j][0]; *(f32x4*)(rp + 512 * j + 4) = a1 * rstd * g4[j][1]; } }
.Lepi_d2:
	s_barrier
	s_add_u32 s90, s26, 0x4000
	s_addc_u32 s91, s27, 0
	global_load_dwordx4 v[188:191], v174, s[90:91]
	global_load_dwordx4 v[192:195], v174, s[90:91] offset:16
	s_add_u32 s90, s26, 0x4800
	s_addc_u32 s91, s27, 0
	global_load_dwordx4 v[196:199], v174, s[90:91]
	global_load_dwordx4 v[200:203], v174, s[90:91] offset:16
	s_add_u32 s90, s26, 0x5000
	s_addc_u32 s91, s27, 0
	global_load_dwordx4 v[104:107], v174, s[90:91]
	global_load_dwordx4 v[108:111], v174, s[90:91] offset:16
	s_add_u32 s90, s26, 0x5800
	s_addc_u32 s91, s27, 0
	global_load_dwordx4 v[112:115], v174, s[90:91]
	global_load_dwordx4 v[120:123], v174, s[90:91] offset:16
	s_cmp_lg_u32 s59, 0
	s_cbranch_scc1 .Lepi_e1
	s_mov_b64 s[86:87], s[82:83]
	v_pk_mul_f32 v[140:141], v[140:141], v[204:205] op_sel_hi:[1,0]
	v_pk_mul_f32 v[142:143], v[142:143], v[204:205] op_sel_hi:[1,0]
	v_pk_mul_f32 v[140:141], v[140:141], v[144:145]
	v_pk_mul_f32 v[142:143], v[142:143], v[146:147]
	v_pk_mul_f32 v[136:137], v[136:137], v[204:205] op_sel_hi:[1,0]
	v_pk_mul_f32 v[138:139], v[138:139], v[204:205] op_sel_hi:[1,0]
	v_pk_mul_f32 v[136:137], v[136:137], v[148:149]
	v_pk_mul_f32 v[138:139], v[138:139], v[150:151]
	v_pk_mul_f32 v[132:133], v[132:133], v[204:205] op_sel_hi:[1,0]
	v_pk_mul_f32 v[134:135], v[134:135], v[204:205] op_sel_hi:[1,0]
	v_pk_mul_f32 v[132:133], v[132:133], v[152:153]
	v_pk_mul_f32 v[134:135], v[134:135], v[154:155]
	v_pk_mul_f32 v[128:129], v[128:129], v[204:205] op_sel_hi:[1,0]
	v_pk_mul_f32 v[130:131], v[130:131], v[204:205] op_sel_hi:[1,0]
	v_pk_mul_f32 v[128:129], v[128:129], v[156:157]
	v_pk_mul_f32 v[130:131], v[130:131], v[158:159]
	global_store_dwordx4 v173, v[140:143], s[86:87]
	global_store_dwordx4 v173, v[136:139], s[86:87] offset:64
	global_store_dwordx4 v173, v[132:135], s[86:87] offset:512
	global_store_dwordx4 v173, v[128:131], s[86:87] offset:576
	s_add_u32 s86, s82, 0x20000
	s_addc_u32 s87, s83, 0
	v_pk_mul_f32 v[124:125], v[124:125], v[206:207] op_sel_hi:[1,0]
	v_pk_mul_f32 v[126:127], v[126:127], v[206:207] op_sel_hi:[1,0]
	v_pk_mul_f32 v[124:125], v[124:125], v[144:145]
	v_pk_mul_f32 v[126:127], v[126:127], v[146:147]
	v_pk_mul_f32 v[116:117], v[116:117], v[206:207] op_sel_hi:[1,0]
	v_pk_mul_f32 v[118:119], v[118:119], v[206:207] op_sel_hi:[1,0]
	v_pk_mul_f32 v[116:117], v[116:117], v[148:149]
	v_pk_mul_f32 v[118:119], v[118:119], v[150:151]
	v_pk_mul_f32 v[100:101], v[100:101], v[206:207] op_sel_hi:[1,0]
	v_pk_mul_f32 v[102:103], v[102:103], v[206:207] op_sel_hi:[1,0]
	v_pk_mul_f32 v[100:101], v[100:101], v[152:153]
	v_pk_mul_f32 v[102:103], v[102:103], v[154:155]
	v_pk_mul_f32 v[96:97], v[96:97], v[206:207] op_sel_hi:[1,0]
	v_pk_mul_f32 v[98:99], v[98:99], v[206:207] op_sel_hi:[1,0]
	v_pk_mul_f32 v[96:97], v[96:97], v[156:157]
	v_pk_mul_f32 v[98:99], v[98:99], v[158:159]
	global_store_dwordx4 v173, v[124:127], s[86:87]
	global_store_dwordx4 v173, v[116:119], s[86:87] offset:64
	global_store_dwordx4 v173, v[100:103], s[86:87] offset:512
	global_store_dwordx4 v173, v[96:99], s[86:87] offset:576
	s_add_u32 s86, s82, 0x40000
	s_addc_u32 s87, s83, 0
	v_pk_mul_f32 v[92:93], v[92:93], v[208:209] op_sel_hi:[1,0]
	v_pk_mul_f32 v[94:95], v[94:95], v[208:209] op_sel_hi:[1,0]
	v_pk_mul_f32 v[92:93], v[92:93], v[144:145]
	v_pk_mul_f32 v[94:95], v[94:95], v[146:147]
	v_pk_mul_f32 v[88:89], v[88:89], v[208:209] op_sel_hi:[1,0]
	v_pk_mul_f32 v[90:91], v[90:91], v[208:209] op_sel_hi:[1,0]
	v_pk_mul_f32 v[88:89], v[88:89], v[148:149]
	v_pk_mul_f32 v[90:91], v[90:91], v[150:151]
	v_pk_mul_f32 v[84:85], v[84:85], v[208:209] op_sel_hi:[1,0]
	v_pk_mul_f32 v[86:87], v[86:87], v[208:209] op_sel_hi:[1,0]
	v_pk_mul_f32 v[84:85], v[84:85], v[152:153]
	v_pk_mul_f32 v[86:87], v[86:87], v[154:155]
	v_pk_mul_f32 v[80:81], v[80:81], v[208:209] op_sel_hi:[1,0]
	v_pk_mul_f32 v[82:83], v[82:83], v[208:209] op_sel_hi:[1,0]
	v_pk_mul_f32 v[80:81], v[80:81], v[156:157]
	v_pk_mul_f32 v[82:83], v[82:83], v[158:159]
	global_store_dwordx4 v173, v[92:95], s[86:87]
	global_store_dwordx4 v173, v[88:91], s[86:87] offset:64
	global_store_dwordx4 v173, v[84:87], s[86:87] offset:512
	global_store_dwordx4 v173, v[80:83], s[86:87] offset:576
	s_add_u32 s86, s82, 0x60000
	s_addc_u32 s87, s83, 0
	v_pk_mul_f32 v[76:77], v[76:77], v[210:211] op_sel_hi:[1,0]
	v_pk_mul_f32 v[78:79], v[78:79], v[210:211] op_sel_hi:[1,0]
	v_pk_mul_f32 v[76:77], v[76:77], v[144:145]
	v_pk_mul_f32 v[78:79], v[78:79], v[146:147]
	v_pk_mul_f32 v[72:73], v[72:73], v[210:211] op_sel_hi:[1,0]
	v_pk_mul_f32 v[74:75], v[74:75], v[210:211] op_sel_hi:[1,0]
	v_pk_mul_f32 v[72:73], v[72:73], v[148:149]
	v_pk_mul_f32 v[74:75], v[74:75], v[150:151]
	v_pk_mul_f32 v[68:69], v[68:69], v[210:211] op_sel_hi:[1,0]
	v_pk_mul_f32 v[70:71], v[70:71], v[210:211] op_sel_hi:[1,0]
	v_pk_mul_f32 v[68:69], v[68:69], v[152:153]
	v_pk_mul_f32 v[70:71], v[70:71], v[154:155]
	v_pk_mul_f32 v[64:65], v[64:65], v[210:211] op_sel_hi:[1,0]
	v_pk_mul_f32 v[66:67], v[66:67], v[210:211] op_sel_hi:[1,0]
	v_pk_mul_f32 v[64:65], v[64:65], v[156:157]
	v_pk_mul_f32 v[66:67], v[66:67], v[158:159]
	global_store_dwordx4 v173, v[76:79], s[86:87]
	global_store_dwordx4 v173, v[72:75], s[86:87] offset:64
	global_store_dwordx4 v173, v[68:71], s[86:87] offset:512
	global_store_dwordx4 v173, v[64:67], s[86:87] offset:576
	s_waitcnt vmcnt(16)
	s_branch .Lepi_e2

; __device__ __forceinline__ void unpack8h(const u32x4 w, f32x4& v0, f32x4& v1) { v0 = (f32x4){h16lo(w.x), h16hi(w.x), h16lo(w.y), h16hi(w.y)}; v1 = (f32x4){h16lo(w.z), h16hi(w.z), h16lo(w.w), h16hi(w.w)}; }
; __device__ __forceinline__ void final_rows(int gw, int lane, const f16* xo, float* out, const float* fg, const float* rowss) {
;     ...
;         for (int rr = 0; rr < 4; ++rr) { const float rstd = rsqrtf(wave_sum(part[rr]) * (1.f / D) + EPS); float* rp = out + (size_t)(r0 + rr) * D + 8 * lane;
; #pragma unroll
;             for (int j = 0; j < 4; ++j) { f32x4 a0, a1; unpack8h(v[rr][j], a0, a1); *(f32x4*)(rp + 512 * j) = a0 * rstd * g4[j][0]; *(f32x4*)(rp + 512 * j + 4) = a1 * rstd * g4[j][1]; } }
.Lepi_e2:
	v_pk_add_f32 v[188:189], v[188:189], v[190:191]
	v_pk_add_f32 v[192:193], v[192:193], v[194:195]
	v_pk_add_f32 v[188:189], v[188:189], v[192:193]
	v_add_f32_e32 v188, v188, v189
	v_pk_add_f32 v[196:197], v[196:197], v[198:199]
	v_pk_add_f32 v[200:201], v[200:201], v[202:203]
	v_pk_add_f32 v[196:197], v[196:197], v[200:201]
	v_add_f32_e32 v196, v196, v197
	v_pk_add_f32 v[104:105], v[104:105], v[106:107]
	v_pk_add_f32 v[108:109], v[108:109], v[110:111]
	v_pk_add_f32 v[104:105], v[104:105], v[108:109]
	v_add_f32_e32 v104, v104, v105
	v_pk_add_f32 v[112:113], v[112:113], v[114:115]
	v_pk_add_f32 v[120:121], v[120:121], v[122:123]
	v_pk_add_f32 v[112:113], v[112:113], v[120:121]
	v_add_f32_e32 v112, v112, v113
	ds_bpermute_b32 v214, v186, v188
	ds_bpermute_b32 v215, v186, v196
	ds_bpermute_b32 v216, v186, v104
	ds_bpermute_b32 v217, v186, v112
	s_waitcnt lgkmcnt(0)
	v_add_f32_e32 v188, v188, v214
	v_add_f32_e32 v196, v196, v215
	v_add_f32_e32 v104, v104, v216
	v_add_f32_e32 v112, v112, v217
	ds_bpermute_b32 v214, v185, v188
	ds_bpermute_b32 v215, v185, v196
	ds_bpermute_b32 v216, v185, v104
	ds_bpermute_b32 v217, v185, v112
	s_waitcnt lgkmcnt(0)
	v_add_f32_e32 v188, v188, v214
	v_add_f32_e32 v196, v196, v215
	v_add_f32_e32 v104, v104, v216
	v_add_f32_e32 v112, v112, v217
	v_mov_b32_e32 v214, s95
	v_mov_b32_e32 v215, s95
	v_mov_b32_e32 v216, s95
	v_mov_b32_e32 v217, s95
	v_fmac_f32_e32 v214, s94, v188
	v_fmac_f32_e32 v215, s94, v196
	v_fmac_f32_e32 v216, s94, v104
	v_fmac_f32_e32 v217, s94, v112
	v_rsq_f32_e32 v204, v214
	v_rsq_f32_e32 v206, v215
	v_rsq_f32_e32 v208, v216
	v_rsq_f32_e32 v210, v217
	s_nop 1
	s_add_u32 s86, s82, 0x100000
	s_addc_u32 s87, s83, 0
	v_pk_mul_f32 v[60:61], v[60:61], v[204:205] op_sel_hi:[1,0]
	v_pk_mul_f32 v[62:63], v[62:63], v[204:205] op_sel_hi:[1,0]
	v_pk_mul_f32 v[60:61], v[60:61], v[144:145]
	v_pk_mul_f32 v[62:63], v[62:63], v[146:147]
	v_pk_mul_f32 v[56:57], v[56:57], v[204:205] op_sel_hi:[1,0]
	v_pk_mul_f32 v[58:59], v[58:59], v[204:205] op_sel_hi:[1,0]
	v_pk_mul_f32 v[56:57], v[56:57], v[148:149]
	v_pk_mul_f32 v[58:59], v[58:59], v[150:151]
	v_pk_mul_f32 v[52:53], v[52:53], v[204:205] op_sel_hi:[1,0]
	v_pk_mul_f32 v[54:55], v[54:55], v[204:205] op_sel_hi:[1,0]
	v_pk_mul_f32 v[52:53], v[52:53], v[152:153]
	v_pk_mul_f32 v[54:55], v[54:55], v[154:155]
	v_pk_mul_f32 v[48:49], v[48:49], v[204:205] op_sel_hi:[1,0]
	v_pk_mul_f32 v[50:51], v[50:51], v[204:205] op_sel_hi:[1,0]
	v_pk_mul_f32 v[48:49], v[48:49], v[156:157]
	v_pk_mul_f32 v[50:51], v[50:51], v[158:159]
	global_store_dwordx4 v173, v[60:63], s[86:87]
	global_store_dwordx4 v173, v[56:59], s[86:87] offset:64
	global_store_dwordx4 v173, v[52:55], s[86:87] offset:512
	global_store_dwordx4 v173, v[48:51], s[86:87] offset:576
	s_add_u32 s86, s82, 0x120000
	s_addc_u32 s87, s83, 0
	v_pk_mul_f32 v[44:45], v[44:45], v[206:207] op_sel_hi:[1,0]
	v_pk_mul_f32 v[46:47], v[46:47], v[206:207] op_sel_hi:[1,0]
	v_pk_mul_f32 v[44:45], v[44:45], v[144:145]
	v_pk_mul_f32 v[46:47], v[46:47], v[146:147]
	v_pk_mul_f32 v[40:41], v[40:41], v[206:207] op_sel_hi:[1,0]
	v_pk_mul_f32 v[42:43], v[42:43], v[206:207] op_sel_hi:[1,0]
	v_pk_mul_f32 v[40:41], v[40:41], v[148:149]
	v_pk_mul_f32 v[42:43], v[42:43], v[150:151]
	v_pk_mul_f32 v[36:37], v[36:37], v[206:207] op_sel_hi:[1,0]
	v_pk_mul_f32 v[38:39], v[38:39], v[206:207] op_sel_hi:[1,0]
	v_pk_mul_f32 v[36:37], v[36:37], v[152:153]
	v_pk_mul_f32 v[38:39], v[38:39], v[154:155]
	v_pk_mul_f32 v[32:33], v[32:33], v[206:207] op_sel_hi:[1,0]
	v_pk_mul_f32 v[34:35], v[34:35], v[206:207] op_sel_hi:[1,0]
	v_pk_mul_f32 v[32:33], v[32:33], v[156:157]
	v_pk_mul_f32 v[34:35], v[34:35], v[158:159]
	global_store_dwordx4 v173, v[44:47], s[86:87]
	global_store_dwordx4 v173, v[40:43], s[86:87] offset:64
	global_store_dwordx4 v173, v[36:39], s[86:87] offset:512
	global_store_dwordx4 v173, v[32:35], s[86:87] offset:576
	s_add_u32 s86, s82, 0x140000
	s_addc_u32 s87, s83, 0
	v_pk_mul_f32 v[28:29], v[28:29], v[208:209] op_sel_hi:[1,0]
	v_pk_mul_f32 v[30:31], v[30:31], v[208:209] op_sel_hi:[1,0]
	v_pk_mul_f32 v[28:29], v[28:29], v[144:145]
	v_pk_mul_f32 v[30:31], v[30:31], v[146:147]
	v_pk_mul_f32 v[24:25], v[24:25], v[208:209] op_sel_hi:[1,0]
	v_pk_mul_f32 v[26:27], v[26:27], v[208:209] op_sel_hi:[1,0]
	v_pk_mul_f32 v[24:25], v[24:25], v[148:149]
	v_pk_mul_f32 v[26:27], v[26:27], v[150:151]
	v_pk_mul_f32 v[20:21], v[20:21], v[208:209] op_sel_hi:[1,0]
	v_pk_mul_f32 v[22:23], v[22:23], v[208:209] op_sel_hi:[1,0]
	v_pk_mul_f32 v[20:21], v[20:21], v[152:153]
	v_pk_mul_f32 v[22:23], v[22:23], v[154:155]
	v_pk_mul_f32 v[16:17], v[16:17], v[208:209] op_sel_hi:[1,0]
	v_pk_mul_f32 v[18:19], v[18:19], v[208:209] op_sel_hi:[1,0]
	v_pk_mul_f32 v[16:17], v[16:17], v[156:157]
	v_pk_mul_f32 v[18:19], v[18:19], v[158:159]
	global_store_dwordx4 v173, v[28:31], s[86:87]
	global_store_dwordx4 v173, v[24:27], s[86:87] offset:64
	global_store_dwordx4 v173, v[20:23], s[86:87] offset:512
	global_store_dwordx4 v173, v[16:19], s[86:87] offset:576
	s_add_u32 s86, s82, 0x160000
	s_addc_u32 s87, s83, 0
	v_pk_mul_f32 v[12:13], v[12:13], v[210:211] op_sel_hi:[1,0]
	v_pk_mul_f32 v[14:15], v[14:15], v[210:211] op_sel_hi:[1,0]
	v_pk_mul_f32 v[12:13], v[12:13], v[144:145]
	v_pk_mul_f32 v[14:15], v[14:15], v[146:147]
	v_pk_mul_f32 v[8:9], v[8:9], v[210:211] op_sel_hi:[1,0]
	v_pk_mul_f32 v[10:11], v[10:11], v[210:211] op_sel_hi:[1,0]
	v_pk_mul_f32 v[8:9], v[8:9], v[148:149]
	v_pk_mul_f32 v[10:11], v[10:11], v[150:151]
	v_pk_mul_f32 v[4:5], v[4:5], v[210:211] op_sel_hi:[1,0]
	v_pk_mul_f32 v[6:7], v[6:7], v[210:211] op_sel_hi:[1,0]
	v_pk_mul_f32 v[4:5], v[4:5], v[152:153]
	v_pk_mul_f32 v[6:7], v[6:7], v[154:155]
	v_pk_mul_f32 v[0:1], v[0:1], v[210:211] op_sel_hi:[1,0]
	v_pk_mul_f32 v[2:3], v[2:3], v[210:211] op_sel_hi:[1,0]
	v_pk_mul_f32 v[0:1], v[0:1], v[156:157]
	v_pk_mul_f32 v[2:3], v[2:3], v[158:159]
	global_store_dwordx4 v173, v[12:15], s[86:87]
	global_store_dwordx4 v173, v[8:11], s[86:87] offset:64
	global_store_dwordx4 v173, v[4:7], s[86:87] offset:512
	global_store_dwordx4 v173, v[0:3], s[86:87] offset:576
	s_and_b64 vcc, exec, s[4:5]
	s_cbranch_vccz .Lepi_nopre
; __device__ __forceinline__ f32x4 ld_nt(const float* p) { return __builtin_nontemporal_load((const f32x4*)p); }
;     __device__ __forceinline__ void operator()(AccRef acc, const Unit& u, int wr, int wc, int fr, int fq) const {
;         int row0 = u.pm * 256 + wr * 64 + fr; asm volatile("" : "+v"(row0)); int col0 = u.pn * 256 + wc * 32 + 8 * fq; asm volatile("" : "+v"(col0));
;         const float* gate = mod + (size_t)(u.pm >= 32 ? 1 : 0) * 3 * D + 2 * D + col0;
;         f32x4 gv[2][2];
; #pragma unroll
;         for (int bj = 0; bj < 2; ++bj)
; #pragma unroll
;             for (int n = 0; n < 2; ++n) gv[bj][n] = *(const f32x4*)(gate + bj * HALF + n * 4);
; #pragma unroll
;         for (int ai = 0; ai < 2; ++ai)
; #pragma unroll
;             for (int mp = 0; mp < 2; ++mp) { f32x4 xv[2][2][2];
; #pragma unroll
;                 for (int mm = 0; mm < 2; ++mm)
; #pragma unroll
;                     for (int bj = 0; bj < 2; ++bj)
; #pragma unroll
;                         for (int n = 0; n < 2; ++n) xv[mm][bj][n] = ld_nt(x + (size_t)(row0 + ai * HALF + (mp * 2 + mm) * 16) * D + col0 + bj * HALF + n * 4);
	v_lshrrev_b32_e32 v251, 4, v184
	v_and_b32_e32 v250, 0x60, v180
	v_lshl_or_b32 v251, v251, 2, v250
	v_lshl_add_u32 v250, s44, 8, v178
	v_lshl_or_b32 v251, s42, 8, v251
	v_readlane_b32 s98, v254, 2
	v_readlane_b32 s99, v254, 3
	v_lshlrev_b32_e32 v250, 13, v250
	v_lshlrev_b32_e32 v251, 2, v251
	s_cmp_gt_i32 s44, 31
	s_cselect_b32 vcc_lo, 0x6000, 0
	s_add_u32 s100, s50, vcc_lo
	s_addc_u32 s101, s51, 0
	s_add_u32 s100, s100, 0x104000
	s_addc_u32 s101, s101, 0
	v_add_u32_e32 v250, v250, v251
	s_nop 1
	global_load_dwordx4 v[218:221], v251, s[100:101]
	global_load_dwordx4 v[222:225], v251, s[100:101] offset:64
	global_load_dwordx4 v[226:229], v251, s[100:101] offset:512
	global_load_dwordx4 v[230:233], v251, s[100:101] offset:576
	global_load_dwordx4 v[234:237], v250, s[98:99] nt
	global_load_dwordx4 v[238:241], v250, s[98:99] offset:64 nt
	global_load_dwordx4 v[242:245], v250, s[98:99] offset:512 nt
	global_load_dwordx4 v[246:249], v250, s[98:99] offset:576 nt
